# GEMM mainloops: LDS-DMA in SGPR-base plus 32-bit VGPR-offset form; 16 per-iteration 64-bit VALU address adds replaced by SALU
# speedup vs baseline: 1.0060x; 1.0011x over previous
; #define PG8_STAGE(bufoff, gbase, voff) do { _Pragma("unroll") for (int _i = 0; _i < 2; ++_i) \
;         __builtin_amdgcn_global_load_lds((const unsigned*)((const char*)(gbase) + (voff)[_i]), (LAS unsigned*)(lds + (bufoff) + ldsw + _i * 8192), 16, 0, 0); } while (0)
; #define PG8_LDA(dst, b, h) do { _Pragma("unroll") for (int m = 0; m < 4; ++m) _Pragma("unroll") for (int k = 0; k < 2; ++k) dst[m][k] = *(const LAS bf16x8*)(lds + PG8_SA(b, h) + aoff + m * 2048 + k * 1024); } while (0)
; #define PG8_LDB(dst, b, h) do { _Pragma("unroll") for (int n = 0; n < 2; ++n) _Pragma("unroll") for (int k = 0; k < 2; ++k) dst[n][k] = *(const LAS bf16x8*)(lds + PG8_SB(b, h) + boff + n * 2048 + k * 1024); } while (0)
; #define PG8_MMA(ai, bj, At, Bt) do { __builtin_amdgcn_s_setprio(1); _Pragma("unroll") for (int m = 0; m < 4; ++m) _Pragma("unroll") for (int n = 0; n < 2; ++n) _Pragma("unroll") for (int k = 0; k < 2; ++k) \
;         acc[ai][bj][m][n] = __builtin_amdgcn_mfma_f32_16x16x32_bf16(Bt[n][k], At[m][k], acc[ai][bj][m][n], 0, 0, 0); __builtin_amdgcn_s_setprio(0); } while (0)
; #define PG8_WAIT_V(n) asm volatile("s_waitcnt vmcnt(" #n ")" ::: "memory")
; #define PG8_WAIT_L(n) asm volatile("s_waitcnt lgkmcnt(" #n ")" ::: "memory")
; #define PG8_BAR __builtin_amdgcn_s_barrier()
; #define PG8_SCHED __builtin_amdgcn_sched_barrier(0)
; template <class Epi>
; __device__ __forceinline__ void gemm_phase(LAS unsigned char* lds, const Gemm g, const StaticOrder& S, const Epi& E) {
;     ...
;         for (int t = 0; t < nt; t += 2) {
;             const bool last = (t == nt - 2);
;             const char* a1 = cA + (size_t)(t + 1) * kstep;
;             const char* a2 = last ? nA : cA + (size_t)(t + 2) * kstep; const char* b2 = last ? nB : cB + (size_t)(t + 2) * kstep;
;             const char* a3 = a2 + kstep; const char* b3 = b2 + kstep;
;             PG8_LDB(B0, 0, 0); PG8_LDB(B1, 0, 1); PG8_SCHED; PG8_LDA(At, 0, 0); PG8_STAGE(PG8_SA(1, 1), a1 + hstepA, voffA);
;             PG8_WAIT_V(8); PG8_WAIT_L(0); PG8_BAR; PG8_MMA(0, 0, At, B0); PG8_MMA(0, 1, At, B1); PG8_BAR; PG8_SCHED;
;             PG8_LDA(At, 0, 1); PG8_STAGE(PG8_SB(0, 0), b2, voffB); PG8_STAGE(PG8_SB(0, 1), b2 + hstepB, voffB); PG8_STAGE(PG8_SA(0, 0), a2, voffA);
;             PG8_WAIT_V(8); PG8_WAIT_L(0); PG8_BAR; PG8_MMA(1, 0, At, B0); PG8_MMA(1, 1, At, B1); PG8_BAR; PG8_SCHED;
.LBB0_233:
	s_add_i32 s83, s26, 2
	s_add_u32 vcc_lo, s12, 0x80
	s_addc_u32 s27, s13, 0
	s_add_i32 s52, 0, 0x10000
	s_cmp_eq_u32 s61, s26
	s_cselect_b32 s27, s3, s27
	s_cselect_b32 s26, s2, vcc_lo
	v_add_u32_e32 v155, s52, v145
	s_cselect_b32 vcc_hi, s25, s82
	s_cselect_b32 vcc_lo, s24, s57
	s_add_i32 s53, 0, 0x14000
	ds_read_b128 v[140:143], v155
	ds_read_b128 v[156:159], v155 offset:1024
	ds_read_b128 v[166:169], v155 offset:2048
	ds_read_b128 v[170:173], v155 offset:3072
	v_add_u32_e32 v155, s53, v145
	ds_read_b128 v[174:177], v155
	ds_read_b128 v[178:181], v155 offset:1024
	ds_read_b128 v[194:197], v155 offset:2048
	ds_read_b128 v[198:201], v155 offset:3072
	s_add_i32 m0, s30, 0xc000
	ds_read_b128 v[202:205], v154
	ds_read_b128 v[206:209], v154 offset:1024
	ds_read_b128 v[210:213], v154 offset:2048
	ds_read_b128 v[214:217], v154 offset:3072
	ds_read_b128 v[218:221], v154 offset:4096
	ds_read_b128 v[222:225], v154 offset:5120
	ds_read_b128 v[226:229], v154 offset:6144
	ds_read_b128 v[234:237], v154 offset:7168
	global_load_lds_dwordx4 v136, s[12:13]
	s_add_i32 m0, s30, 0xe000
	s_nop 0
	global_load_lds_dwordx4 v138, s[12:13]
	s_waitcnt vmcnt(8)
	s_waitcnt lgkmcnt(0)
	s_setprio 1
	s_barrier
	v_mfma_f32_16x16x32_bf16 v[126:129], v[140:143], v[202:205], v[126:129]
	v_mfma_f32_16x16x32_bf16 v[122:125], v[166:169], v[202:205], v[122:125]
	v_mfma_f32_16x16x32_bf16 v[110:113], v[140:143], v[210:213], v[110:113]
	v_mfma_f32_16x16x32_bf16 v[106:109], v[166:169], v[210:213], v[106:109]
	v_mfma_f32_16x16x32_bf16 v[94:97], v[140:143], v[218:221], v[94:97]
	v_mfma_f32_16x16x32_bf16 v[90:93], v[166:169], v[218:221], v[90:93]
	v_mfma_f32_16x16x32_bf16 v[78:81], v[140:143], v[226:229], v[78:81]
	v_mfma_f32_16x16x32_bf16 v[74:77], v[166:169], v[226:229], v[74:77]
	v_mfma_f32_16x16x32_bf16 v[126:129], v[156:159], v[206:209], v[126:129]
	v_mfma_f32_16x16x32_bf16 v[122:125], v[170:173], v[206:209], v[122:125]
	v_mfma_f32_16x16x32_bf16 v[110:113], v[156:159], v[214:217], v[110:113]
	v_mfma_f32_16x16x32_bf16 v[106:109], v[170:173], v[214:217], v[106:109]
	v_mfma_f32_16x16x32_bf16 v[94:97], v[156:159], v[222:225], v[94:97]
	v_mfma_f32_16x16x32_bf16 v[90:93], v[170:173], v[222:225], v[90:93]
	v_mfma_f32_16x16x32_bf16 v[78:81], v[156:159], v[234:237], v[78:81]
	v_mfma_f32_16x16x32_bf16 v[74:77], v[170:173], v[234:237], v[74:77]
	v_mfma_f32_16x16x32_bf16 v[118:121], v[174:177], v[202:205], v[118:121]
	v_mfma_f32_16x16x32_bf16 v[114:117], v[194:197], v[202:205], v[114:117]
	v_mfma_f32_16x16x32_bf16 v[102:105], v[174:177], v[210:213], v[102:105]
	v_mfma_f32_16x16x32_bf16 v[98:101], v[194:197], v[210:213], v[98:101]
	v_mfma_f32_16x16x32_bf16 v[86:89], v[174:177], v[218:221], v[86:89]
	v_mfma_f32_16x16x32_bf16 v[82:85], v[194:197], v[218:221], v[82:85]
	v_mfma_f32_16x16x32_bf16 v[70:73], v[174:177], v[226:229], v[70:73]
	v_mfma_f32_16x16x32_bf16 v[66:69], v[194:197], v[226:229], v[66:69]
	v_mfma_f32_16x16x32_bf16 v[118:121], v[178:181], v[206:209], v[118:121]
	v_mfma_f32_16x16x32_bf16 v[114:117], v[198:201], v[206:209], v[114:117]
	v_mfma_f32_16x16x32_bf16 v[102:105], v[178:181], v[214:217], v[102:105]
	v_mfma_f32_16x16x32_bf16 v[98:101], v[198:201], v[214:217], v[98:101]
	v_mfma_f32_16x16x32_bf16 v[86:89], v[178:181], v[222:225], v[86:89]
	v_mfma_f32_16x16x32_bf16 v[82:85], v[198:201], v[222:225], v[82:85]
	v_mfma_f32_16x16x32_bf16 v[70:73], v[178:181], v[234:237], v[70:73]
	v_mfma_f32_16x16x32_bf16 v[66:69], v[198:201], v[234:237], v[66:69]
	s_barrier
	s_setprio 0
	s_add_i32 s52, s52, s41
	s_mov_b32 m0, s52
	ds_read_b128 v[202:205], v154 offset:16384
	ds_read_b128 v[206:209], v154 offset:17408
	ds_read_b128 v[210:213], v154 offset:18432
	ds_read_b128 v[214:217], v154 offset:19456
	ds_read_b128 v[218:221], v154 offset:20480
	ds_read_b128 v[222:225], v154 offset:21504
	ds_read_b128 v[226:229], v154 offset:22528
	ds_read_b128 v[234:237], v154 offset:23552
	global_load_lds_dwordx4 v0, vcc
	s_add_i32 m0, s52, 0x2000
	s_add_i32 s52, s53, s41
	global_load_lds_dwordx4 v134, vcc
	s_add_u32 vcc_lo, vcc_lo, s23
	s_addc_u32 vcc_hi, vcc_hi, 0
	s_mov_b32 m0, s52
	s_nop 0
	global_load_lds_dwordx4 v0, vcc
	s_add_i32 m0, s52, 0x2000
	s_nop 0
	global_load_lds_dwordx4 v134, vcc
	s_mov_b32 m0, s30
	s_nop 0
	global_load_lds_dwordx4 v130, s[26:27]
	s_mov_b32 m0, s31
	s_nop 0
	global_load_lds_dwordx4 v132, s[26:27]
	s_waitcnt vmcnt(8)
	s_waitcnt lgkmcnt(0)
	s_setprio 1
	s_barrier
	v_mfma_f32_16x16x32_bf16 v[62:65], v[140:143], v[202:205], v[62:65]
	v_mfma_f32_16x16x32_bf16 v[58:61], v[166:169], v[202:205], v[58:61]
	v_mfma_f32_16x16x32_bf16 v[46:49], v[140:143], v[210:213], v[46:49]
	v_mfma_f32_16x16x32_bf16 v[42:45], v[166:169], v[210:213], v[42:45]
	v_mfma_f32_16x16x32_bf16 v[30:33], v[140:143], v[218:221], v[30:33]
	v_mfma_f32_16x16x32_bf16 v[26:29], v[166:169], v[218:221], v[26:29]
	v_mfma_f32_16x16x32_bf16 v[14:17], v[140:143], v[226:229], v[14:17]
	v_mfma_f32_16x16x32_bf16 v[10:13], v[166:169], v[226:229], v[10:13]
	v_mfma_f32_16x16x32_bf16 v[62:65], v[156:159], v[206:209], v[62:65]
	v_mfma_f32_16x16x32_bf16 v[58:61], v[170:173], v[206:209], v[58:61]
	v_mfma_f32_16x16x32_bf16 v[46:49], v[156:159], v[214:217], v[46:49]
	v_mfma_f32_16x16x32_bf16 v[42:45], v[170:173], v[214:217], v[42:45]
	v_mfma_f32_16x16x32_bf16 v[30:33], v[156:159], v[222:225], v[30:33]
	v_mfma_f32_16x16x32_bf16 v[26:29], v[170:173], v[222:225], v[26:29]
	v_mfma_f32_16x16x32_bf16 v[14:17], v[156:159], v[234:237], v[14:17]
	v_mfma_f32_16x16x32_bf16 v[10:13], v[170:173], v[234:237], v[10:13]
	v_mfma_f32_16x16x32_bf16 v[54:57], v[174:177], v[202:205], v[54:57]
	v_mfma_f32_16x16x32_bf16 v[50:53], v[194:197], v[202:205], v[50:53]
	v_mfma_f32_16x16x32_bf16 v[38:41], v[174:177], v[210:213], v[38:41]
	v_mfma_f32_16x16x32_bf16 v[34:37], v[194:197], v[210:213], v[34:37]
	v_mfma_f32_16x16x32_bf16 v[22:25], v[174:177], v[218:221], v[22:25]
	v_mfma_f32_16x16x32_bf16 v[18:21], v[194:197], v[218:221], v[18:21]
	v_mfma_f32_16x16x32_bf16 v[6:9], v[174:177], v[226:229], v[6:9]
	v_mfma_f32_16x16x32_bf16 v[2:5], v[194:197], v[226:229], v[2:5]
	v_mfma_f32_16x16x32_bf16 v[54:57], v[178:181], v[206:209], v[54:57]
	v_mfma_f32_16x16x32_bf16 v[50:53], v[198:201], v[206:209], v[50:53]
	v_mfma_f32_16x16x32_bf16 v[38:41], v[178:181], v[214:217], v[38:41]
	v_mfma_f32_16x16x32_bf16 v[34:37], v[198:201], v[214:217], v[34:37]
	v_mfma_f32_16x16x32_bf16 v[22:25], v[178:181], v[222:225], v[22:25]
	v_mfma_f32_16x16x32_bf16 v[18:21], v[198:201], v[222:225], v[18:21]
	v_mfma_f32_16x16x32_bf16 v[6:9], v[178:181], v[234:237], v[6:9]
	v_mfma_f32_16x16x32_bf16 v[2:5], v[198:201], v[234:237], v[2:5]
	s_barrier
; #define PG8_STAGE(bufoff, gbase, voff) do { _Pragma("unroll") for (int _i = 0; _i < 2; ++_i) \
;         __builtin_amdgcn_global_load_lds((const unsigned*)((const char*)(gbase) + (voff)[_i]), (LAS unsigned*)(lds + (bufoff) + ldsw + _i * 8192), 16, 0, 0); } while (0)
; #define PG8_LDA(dst, b, h) do { _Pragma("unroll") for (int m = 0; m < 4; ++m) _Pragma("unroll") for (int k = 0; k < 2; ++k) dst[m][k] = *(const LAS bf16x8*)(lds + PG8_SA(b, h) + aoff + m * 2048 + k * 1024); } while (0)
; #define PG8_LDB(dst, b, h) do { _Pragma("unroll") for (int n = 0; n < 2; ++n) _Pragma("unroll") for (int k = 0; k < 2; ++k) dst[n][k] = *(const LAS bf16x8*)(lds + PG8_SB(b, h) + boff + n * 2048 + k * 1024); } while (0)
; #define PG8_MMA(ai, bj, At, Bt) do { __builtin_amdgcn_s_setprio(1); _Pragma("unroll") for (int m = 0; m < 4; ++m) _Pragma("unroll") for (int n = 0; n < 2; ++n) _Pragma("unroll") for (int k = 0; k < 2; ++k) \
;         acc[ai][bj][m][n] = __builtin_amdgcn_mfma_f32_16x16x32_bf16(Bt[n][k], At[m][k], acc[ai][bj][m][n], 0, 0, 0); __builtin_amdgcn_s_setprio(0); } while (0)
; #define PG8_WAIT_V(n) asm volatile("s_waitcnt vmcnt(" #n ")" ::: "memory")
; #define PG8_WAIT_L(n) asm volatile("s_waitcnt lgkmcnt(" #n ")" ::: "memory")
; #define PG8_BAR __builtin_amdgcn_s_barrier()
; #define PG8_SCHED __builtin_amdgcn_sched_barrier(0)
; template <class Epi>
; __device__ __forceinline__ void gemm_phase(LAS unsigned char* lds, const Gemm g, const StaticOrder& S, const Epi& E) {
;     ...
;             PG8_LDB(B0, 1, 0); PG8_LDB(B1, 1, 1); PG8_SCHED; PG8_LDA(At, 1, 0); PG8_STAGE(PG8_SA(0, 1), a2 + hstepA, voffA);
;             PG8_WAIT_V(8); PG8_WAIT_L(0); PG8_BAR; PG8_MMA(0, 0, At, B0); PG8_MMA(0, 1, At, B1); PG8_BAR; PG8_SCHED;
;             PG8_LDA(At, 1, 1); PG8_STAGE(PG8_SB(1, 0), b3, voffB); PG8_STAGE(PG8_SB(1, 1), b3 + hstepB, voffB); PG8_STAGE(PG8_SA(1, 0), a3, voffA);
;             PG8_WAIT_V(8); PG8_WAIT_L(0); PG8_BAR; PG8_MMA(1, 0, At, B0); PG8_MMA(1, 1, At, B1); PG8_BAR; PG8_SCHED;
;         }
;         if (wr == 0) PG8_BAR;
	s_setprio 0
	s_add_i32 s52, 0, 0x18000
	v_add_u32_e32 v155, s52, v145
	s_add_i32 s53, 0, 0x1c000
	ds_read_b128 v[140:143], v155
	ds_read_b128 v[156:159], v155 offset:1024
	ds_read_b128 v[166:169], v155 offset:2048
	ds_read_b128 v[170:173], v155 offset:3072
	v_add_u32_e32 v155, s53, v145
	ds_read_b128 v[174:177], v155
	ds_read_b128 v[178:181], v155 offset:1024
	ds_read_b128 v[194:197], v155 offset:2048
	ds_read_b128 v[198:201], v155 offset:3072
	s_add_u32 s26, s26, s78
	s_addc_u32 s27, s27, 0
	s_mov_b32 m0, s64
	ds_read_b128 v[202:205], v154 offset:32768
	ds_read_b128 v[206:209], v154 offset:33792
	ds_read_b128 v[210:213], v154 offset:34816
	ds_read_b128 v[214:217], v154 offset:35840
	ds_read_b128 v[218:221], v154 offset:36864
	ds_read_b128 v[222:225], v154 offset:37888
	ds_read_b128 v[226:229], v154 offset:38912
	ds_read_b128 v[234:237], v154 offset:39936
	global_load_lds_dwordx4 v130, s[26:27]
	s_mov_b32 m0, s85
	s_nop 0
	global_load_lds_dwordx4 v132, s[26:27]
	s_waitcnt vmcnt(8)
	s_waitcnt lgkmcnt(0)
	s_setprio 1
	s_barrier
	v_mfma_f32_16x16x32_bf16 v[126:129], v[140:143], v[202:205], v[126:129]
	v_mfma_f32_16x16x32_bf16 v[122:125], v[166:169], v[202:205], v[122:125]
	v_mfma_f32_16x16x32_bf16 v[110:113], v[140:143], v[210:213], v[110:113]
	v_mfma_f32_16x16x32_bf16 v[106:109], v[166:169], v[210:213], v[106:109]
	v_mfma_f32_16x16x32_bf16 v[94:97], v[140:143], v[218:221], v[94:97]
	v_mfma_f32_16x16x32_bf16 v[90:93], v[166:169], v[218:221], v[90:93]
	v_mfma_f32_16x16x32_bf16 v[78:81], v[140:143], v[226:229], v[78:81]
	v_mfma_f32_16x16x32_bf16 v[74:77], v[166:169], v[226:229], v[74:77]
	v_mfma_f32_16x16x32_bf16 v[126:129], v[156:159], v[206:209], v[126:129]
	v_mfma_f32_16x16x32_bf16 v[122:125], v[170:173], v[206:209], v[122:125]
	v_mfma_f32_16x16x32_bf16 v[110:113], v[156:159], v[214:217], v[110:113]
	v_mfma_f32_16x16x32_bf16 v[106:109], v[170:173], v[214:217], v[106:109]
	v_mfma_f32_16x16x32_bf16 v[94:97], v[156:159], v[222:225], v[94:97]
	v_mfma_f32_16x16x32_bf16 v[90:93], v[170:173], v[222:225], v[90:93]
	v_mfma_f32_16x16x32_bf16 v[78:81], v[156:159], v[234:237], v[78:81]
	v_mfma_f32_16x16x32_bf16 v[74:77], v[170:173], v[234:237], v[74:77]
	v_mfma_f32_16x16x32_bf16 v[118:121], v[174:177], v[202:205], v[118:121]
	v_mfma_f32_16x16x32_bf16 v[114:117], v[194:197], v[202:205], v[114:117]
	v_mfma_f32_16x16x32_bf16 v[102:105], v[174:177], v[210:213], v[102:105]
	v_mfma_f32_16x16x32_bf16 v[98:101], v[194:197], v[210:213], v[98:101]
	v_mfma_f32_16x16x32_bf16 v[86:89], v[174:177], v[218:221], v[86:89]
	v_mfma_f32_16x16x32_bf16 v[82:85], v[194:197], v[218:221], v[82:85]
	v_mfma_f32_16x16x32_bf16 v[70:73], v[174:177], v[226:229], v[70:73]
	v_mfma_f32_16x16x32_bf16 v[66:69], v[194:197], v[226:229], v[66:69]
	v_mfma_f32_16x16x32_bf16 v[118:121], v[178:181], v[206:209], v[118:121]
	v_mfma_f32_16x16x32_bf16 v[114:117], v[198:201], v[206:209], v[114:117]
	v_mfma_f32_16x16x32_bf16 v[102:105], v[178:181], v[214:217], v[102:105]
	v_mfma_f32_16x16x32_bf16 v[98:101], v[198:201], v[214:217], v[98:101]
	v_mfma_f32_16x16x32_bf16 v[86:89], v[178:181], v[222:225], v[86:89]
	v_mfma_f32_16x16x32_bf16 v[82:85], v[198:201], v[222:225], v[82:85]
	v_mfma_f32_16x16x32_bf16 v[70:73], v[178:181], v[234:237], v[70:73]
	v_mfma_f32_16x16x32_bf16 v[66:69], v[198:201], v[234:237], v[66:69]
	s_barrier
	s_setprio 0
	s_add_i32 s32, s52, s41
	s_sub_u32 vcc_lo, vcc_lo, s23
	s_subb_u32 vcc_hi, vcc_hi, 0
	s_add_u32 vcc_lo, vcc_lo, 0x80
	s_addc_u32 vcc_hi, vcc_hi, 0
	s_mov_b32 m0, s32
	ds_read_b128 v[202:205], v154 offset:49152
	ds_read_b128 v[206:209], v154 offset:50176
	ds_read_b128 v[210:213], v154 offset:51200
	ds_read_b128 v[214:217], v154 offset:52224
	ds_read_b128 v[218:221], v154 offset:53248
	ds_read_b128 v[222:225], v154 offset:54272
	ds_read_b128 v[226:229], v154 offset:55296
	ds_read_b128 v[234:237], v154 offset:56320
	global_load_lds_dwordx4 v0, vcc
	s_add_i32 m0, s32, 0x2000
	s_add_i32 s32, s53, s41
	global_load_lds_dwordx4 v134, vcc
	s_add_u32 vcc_lo, vcc_lo, s23
	s_addc_u32 vcc_hi, vcc_hi, 0
	s_mov_b32 m0, s32
	s_nop 0
	global_load_lds_dwordx4 v0, vcc
	s_add_i32 m0, s32, 0x2000
	s_sub_u32 s26, s26, s78
	s_subb_u32 s27, s27, 0
	global_load_lds_dwordx4 v134, vcc
	s_add_u32 s26, s26, 0x80
	s_addc_u32 s27, s27, 0
	s_mov_b32 m0, s92
	s_nop 0
	global_load_lds_dwordx4 v130, s[26:27]
	s_mov_b32 m0, s93
	s_nop 0
	global_load_lds_dwordx4 v132, s[26:27]
	s_waitcnt vmcnt(8)
	s_waitcnt lgkmcnt(0)
	s_setprio 1
	s_barrier
	v_mfma_f32_16x16x32_bf16 v[62:65], v[140:143], v[202:205], v[62:65]
	v_mfma_f32_16x16x32_bf16 v[58:61], v[166:169], v[202:205], v[58:61]
	v_mfma_f32_16x16x32_bf16 v[46:49], v[140:143], v[210:213], v[46:49]
	v_mfma_f32_16x16x32_bf16 v[42:45], v[166:169], v[210:213], v[42:45]
	v_mfma_f32_16x16x32_bf16 v[30:33], v[140:143], v[218:221], v[30:33]
	v_mfma_f32_16x16x32_bf16 v[26:29], v[166:169], v[218:221], v[26:29]
	v_mfma_f32_16x16x32_bf16 v[14:17], v[140:143], v[226:229], v[14:17]
	v_mfma_f32_16x16x32_bf16 v[10:13], v[166:169], v[226:229], v[10:13]
	v_mfma_f32_16x16x32_bf16 v[62:65], v[156:159], v[206:209], v[62:65]
	v_mfma_f32_16x16x32_bf16 v[58:61], v[170:173], v[206:209], v[58:61]
	v_mfma_f32_16x16x32_bf16 v[46:49], v[156:159], v[214:217], v[46:49]
	v_mfma_f32_16x16x32_bf16 v[42:45], v[170:173], v[214:217], v[42:45]
	v_mfma_f32_16x16x32_bf16 v[30:33], v[156:159], v[222:225], v[30:33]
	v_mfma_f32_16x16x32_bf16 v[26:29], v[170:173], v[222:225], v[26:29]
	v_mfma_f32_16x16x32_bf16 v[14:17], v[156:159], v[234:237], v[14:17]
	v_mfma_f32_16x16x32_bf16 v[10:13], v[170:173], v[234:237], v[10:13]
	v_mfma_f32_16x16x32_bf16 v[54:57], v[174:177], v[202:205], v[54:57]
	v_mfma_f32_16x16x32_bf16 v[50:53], v[194:197], v[202:205], v[50:53]
	v_mfma_f32_16x16x32_bf16 v[38:41], v[174:177], v[210:213], v[38:41]
	v_mfma_f32_16x16x32_bf16 v[34:37], v[194:197], v[210:213], v[34:37]
	v_mfma_f32_16x16x32_bf16 v[22:25], v[174:177], v[218:221], v[22:25]
	v_mfma_f32_16x16x32_bf16 v[18:21], v[194:197], v[218:221], v[18:21]
	v_mfma_f32_16x16x32_bf16 v[6:9], v[174:177], v[226:229], v[6:9]
	v_mfma_f32_16x16x32_bf16 v[2:5], v[194:197], v[226:229], v[2:5]
	v_mfma_f32_16x16x32_bf16 v[54:57], v[178:181], v[206:209], v[54:57]
	v_mfma_f32_16x16x32_bf16 v[50:53], v[198:201], v[206:209], v[50:53]
	v_mfma_f32_16x16x32_bf16 v[38:41], v[178:181], v[214:217], v[38:41]
	v_mfma_f32_16x16x32_bf16 v[34:37], v[198:201], v[214:217], v[34:37]
	v_mfma_f32_16x16x32_bf16 v[22:25], v[178:181], v[222:225], v[22:25]
	v_mfma_f32_16x16x32_bf16 v[18:21], v[198:201], v[222:225], v[18:21]
	v_mfma_f32_16x16x32_bf16 v[6:9], v[178:181], v[234:237], v[6:9]
	v_mfma_f32_16x16x32_bf16 v[2:5], v[198:201], v[234:237], v[2:5]
	s_barrier
	s_setprio 0
	s_add_u32 s12, s12, 0x100
	s_addc_u32 s13, s13, 0
	s_add_u32 s57, s57, 0x100
	s_addc_u32 s82, s82, 0
	s_cmp_ge_u32 s83, s80
	s_mov_b32 s26, s83
	s_cbranch_scc0 .LBB0_233
	s_and_b64 vcc, exec, s[74:75]
	s_cbranch_vccz .LBB0_236
	s_barrier

; #define PG8_STAGE(bufoff, gbase, voff) do { _Pragma("unroll") for (int _i = 0; _i < 2; ++_i) \
;         __builtin_amdgcn_global_load_lds((const unsigned*)((const char*)(gbase) + (voff)[_i]), (LAS unsigned*)(lds + (bufoff) + ldsw + _i * 8192), 16, 0, 0); } while (0)
; #define PG8_LDA(dst, b, h) do { _Pragma("unroll") for (int m = 0; m < 4; ++m) _Pragma("unroll") for (int k = 0; k < 2; ++k) dst[m][k] = *(const LAS bf16x8*)(lds + PG8_SA(b, h) + aoff + m * 2048 + k * 1024); } while (0)
; #define PG8_LDB(dst, b, h) do { _Pragma("unroll") for (int n = 0; n < 2; ++n) _Pragma("unroll") for (int k = 0; k < 2; ++k) dst[n][k] = *(const LAS bf16x8*)(lds + PG8_SB(b, h) + boff + n * 2048 + k * 1024); } while (0)
; #define PG8_MMA(ai, bj, At, Bt) do { __builtin_amdgcn_s_setprio(1); _Pragma("unroll") for (int m = 0; m < 4; ++m) _Pragma("unroll") for (int n = 0; n < 2; ++n) _Pragma("unroll") for (int k = 0; k < 2; ++k) \
;         acc[ai][bj][m][n] = __builtin_amdgcn_mfma_f32_16x16x32_bf16(Bt[n][k], At[m][k], acc[ai][bj][m][n], 0, 0, 0); __builtin_amdgcn_s_setprio(0); } while (0)
; #define PG8_WAIT_V(n) asm volatile("s_waitcnt vmcnt(" #n ")" ::: "memory")
; #define PG8_WAIT_L(n) asm volatile("s_waitcnt lgkmcnt(" #n ")" ::: "memory")
; #define PG8_BAR __builtin_amdgcn_s_barrier()
; #define PG8_SCHED __builtin_amdgcn_sched_barrier(0)
; template <class Epi>
; __device__ __forceinline__ void gemm_phase(LAS unsigned char* lds, const Gemm g, const StaticOrder& S, const Epi& E) {
;     ...
;         for (int t = 0; t < nt; t += 2) {
;             const bool last = (t == nt - 2);
;             const char* a1 = cA + (size_t)(t + 1) * kstep;
;             const char* a2 = last ? nA : cA + (size_t)(t + 2) * kstep; const char* b2 = last ? nB : cB + (size_t)(t + 2) * kstep;
;             const char* a3 = a2 + kstep; const char* b3 = b2 + kstep;
;             PG8_LDB(B0, 0, 0); PG8_LDB(B1, 0, 1); PG8_SCHED; PG8_LDA(At, 0, 0); PG8_STAGE(PG8_SA(1, 1), a1 + hstepA, voffA);
;             PG8_WAIT_V(8); PG8_WAIT_L(0); PG8_BAR; PG8_MMA(0, 0, At, B0); PG8_MMA(0, 1, At, B1); PG8_BAR; PG8_SCHED;
;             PG8_LDA(At, 0, 1); PG8_STAGE(PG8_SB(0, 0), b2, voffB); PG8_STAGE(PG8_SB(0, 1), b2 + hstepB, voffB); PG8_STAGE(PG8_SA(0, 0), a2, voffA);
;             PG8_WAIT_V(8); PG8_WAIT_L(0); PG8_BAR; PG8_MMA(1, 0, At, B0); PG8_MMA(1, 1, At, B1); PG8_BAR; PG8_SCHED;
.LBB0_295:
	s_add_u32 s26, s24, 0xfff80080
	s_addc_u32 s27, s25, -1
	s_add_i32 s50, 0, 0x10000
	s_cmp_eq_u32 s49, 28
	s_cselect_b32 s35, s13, s27
	s_cselect_b32 s34, s43, s26
	s_cselect_b32 s27, s11, s48
	s_cselect_b32 s26, s46, s47
	s_add_i32 s56, 0, 0x14000
	v_add_u32_e32 v156, s50, v145
	v_add_u32_e32 v160, s56, v145
	ds_read_b128 v[140:143], v156
	ds_read_b128 v[148:151], v156 offset:1024
	ds_read_b128 v[152:155], v156 offset:2048
	ds_read_b128 v[156:159], v156 offset:3072
	ds_read_b128 v[166:169], v160
	ds_read_b128 v[170:173], v160 offset:1024
	ds_read_b128 v[174:177], v160 offset:2048
	ds_read_b128 v[178:181], v160 offset:3072
	s_add_i32 m0, s19, 0xc000
	ds_read_b128 v[194:197], v147
	ds_read_b128 v[198:201], v147 offset:1024
	ds_read_b128 v[202:205], v147 offset:2048
	ds_read_b128 v[206:209], v147 offset:3072
	ds_read_b128 v[210:213], v147 offset:4096
	ds_read_b128 v[214:217], v147 offset:5120
	ds_read_b128 v[218:221], v147 offset:6144
	ds_read_b128 v[222:225], v147 offset:7168
	global_load_lds_dwordx4 v136, s[24:25]
	s_add_i32 m0, s19, 0xe000
	s_nop 0
	global_load_lds_dwordx4 v138, s[24:25]
	s_waitcnt vmcnt(8)
	s_waitcnt lgkmcnt(0)
	s_setprio 1
	s_barrier
	v_mfma_f32_16x16x32_bf16 v[126:129], v[140:143], v[194:197], v[126:129]
	v_mfma_f32_16x16x32_bf16 v[122:125], v[152:155], v[194:197], v[122:125]
	v_mfma_f32_16x16x32_bf16 v[110:113], v[140:143], v[202:205], v[110:113]
	v_mfma_f32_16x16x32_bf16 v[106:109], v[152:155], v[202:205], v[106:109]
	v_mfma_f32_16x16x32_bf16 v[94:97], v[140:143], v[210:213], v[94:97]
	v_mfma_f32_16x16x32_bf16 v[90:93], v[152:155], v[210:213], v[90:93]
	v_mfma_f32_16x16x32_bf16 v[78:81], v[140:143], v[218:221], v[78:81]
	v_mfma_f32_16x16x32_bf16 v[74:77], v[152:155], v[218:221], v[74:77]
	v_mfma_f32_16x16x32_bf16 v[126:129], v[148:151], v[198:201], v[126:129]
	v_mfma_f32_16x16x32_bf16 v[122:125], v[156:159], v[198:201], v[122:125]
	v_mfma_f32_16x16x32_bf16 v[110:113], v[148:151], v[206:209], v[110:113]
	v_mfma_f32_16x16x32_bf16 v[106:109], v[156:159], v[206:209], v[106:109]
	v_mfma_f32_16x16x32_bf16 v[94:97], v[148:151], v[214:217], v[94:97]
	v_mfma_f32_16x16x32_bf16 v[90:93], v[156:159], v[214:217], v[90:93]
	v_mfma_f32_16x16x32_bf16 v[78:81], v[148:151], v[222:225], v[78:81]
	v_mfma_f32_16x16x32_bf16 v[74:77], v[156:159], v[222:225], v[74:77]
	v_mfma_f32_16x16x32_bf16 v[118:121], v[166:169], v[194:197], v[118:121]
	v_mfma_f32_16x16x32_bf16 v[114:117], v[174:177], v[194:197], v[114:117]
	v_mfma_f32_16x16x32_bf16 v[102:105], v[166:169], v[202:205], v[102:105]
	v_mfma_f32_16x16x32_bf16 v[98:101], v[174:177], v[202:205], v[98:101]
	v_mfma_f32_16x16x32_bf16 v[86:89], v[166:169], v[210:213], v[86:89]
	v_mfma_f32_16x16x32_bf16 v[82:85], v[174:177], v[210:213], v[82:85]
	v_mfma_f32_16x16x32_bf16 v[70:73], v[166:169], v[218:221], v[70:73]
	v_mfma_f32_16x16x32_bf16 v[66:69], v[174:177], v[218:221], v[66:69]
	v_mfma_f32_16x16x32_bf16 v[118:121], v[170:173], v[198:201], v[118:121]
	v_mfma_f32_16x16x32_bf16 v[114:117], v[178:181], v[198:201], v[114:117]
	v_mfma_f32_16x16x32_bf16 v[102:105], v[170:173], v[206:209], v[102:105]
	v_mfma_f32_16x16x32_bf16 v[98:101], v[178:181], v[206:209], v[98:101]
	v_mfma_f32_16x16x32_bf16 v[86:89], v[170:173], v[214:217], v[86:89]
	v_mfma_f32_16x16x32_bf16 v[82:85], v[178:181], v[214:217], v[82:85]
	v_mfma_f32_16x16x32_bf16 v[70:73], v[170:173], v[222:225], v[70:73]
	v_mfma_f32_16x16x32_bf16 v[66:69], v[178:181], v[222:225], v[66:69]
	s_barrier
	s_setprio 0
	s_add_i32 s50, s50, s23
	s_mov_b32 m0, s50
	ds_read_b128 v[194:197], v147 offset:16384
	ds_read_b128 v[198:201], v147 offset:17408
	ds_read_b128 v[202:205], v147 offset:18432
	ds_read_b128 v[206:209], v147 offset:19456
	ds_read_b128 v[210:213], v147 offset:20480
	ds_read_b128 v[214:217], v147 offset:21504
	ds_read_b128 v[218:221], v147 offset:22528
	ds_read_b128 v[222:225], v147 offset:23552
	global_load_lds_dwordx4 v0, s[26:27]
	s_add_i32 m0, s50, 0x2000
	s_add_u32 s50, s26, 0x80000
	s_addc_u32 s51, s27, 0
	s_add_i32 s56, s56, s23
	global_load_lds_dwordx4 v130, s[26:27]
	s_mov_b32 m0, s56
	s_nop 0
	global_load_lds_dwordx4 v0, s[50:51]
	s_add_i32 m0, s56, 0x2000
	s_nop 0
	global_load_lds_dwordx4 v130, s[50:51]
	s_mov_b32 m0, s19
	s_nop 0
	global_load_lds_dwordx4 v134, s[34:35]
	s_mov_b32 m0, s31
	s_nop 0
	global_load_lds_dwordx4 v132, s[34:35]
	s_waitcnt vmcnt(8)
	s_waitcnt lgkmcnt(0)
	s_setprio 1
	s_barrier
	v_mfma_f32_16x16x32_bf16 v[62:65], v[140:143], v[194:197], v[62:65]
	v_mfma_f32_16x16x32_bf16 v[58:61], v[152:155], v[194:197], v[58:61]
	v_mfma_f32_16x16x32_bf16 v[46:49], v[140:143], v[202:205], v[46:49]
	v_mfma_f32_16x16x32_bf16 v[42:45], v[152:155], v[202:205], v[42:45]
	v_mfma_f32_16x16x32_bf16 v[30:33], v[140:143], v[210:213], v[30:33]
	v_mfma_f32_16x16x32_bf16 v[26:29], v[152:155], v[210:213], v[26:29]
	v_mfma_f32_16x16x32_bf16 v[14:17], v[140:143], v[218:221], v[14:17]
	v_mfma_f32_16x16x32_bf16 v[10:13], v[152:155], v[218:221], v[10:13]
	v_mfma_f32_16x16x32_bf16 v[62:65], v[148:151], v[198:201], v[62:65]
	v_mfma_f32_16x16x32_bf16 v[58:61], v[156:159], v[198:201], v[58:61]
	v_mfma_f32_16x16x32_bf16 v[46:49], v[148:151], v[206:209], v[46:49]
	v_mfma_f32_16x16x32_bf16 v[42:45], v[156:159], v[206:209], v[42:45]
	v_mfma_f32_16x16x32_bf16 v[30:33], v[148:151], v[214:217], v[30:33]
	v_mfma_f32_16x16x32_bf16 v[26:29], v[156:159], v[214:217], v[26:29]
	v_mfma_f32_16x16x32_bf16 v[14:17], v[148:151], v[222:225], v[14:17]
	v_mfma_f32_16x16x32_bf16 v[10:13], v[156:159], v[222:225], v[10:13]
	v_mfma_f32_16x16x32_bf16 v[54:57], v[166:169], v[194:197], v[54:57]
	v_mfma_f32_16x16x32_bf16 v[50:53], v[174:177], v[194:197], v[50:53]
	v_mfma_f32_16x16x32_bf16 v[38:41], v[166:169], v[202:205], v[38:41]
	v_mfma_f32_16x16x32_bf16 v[34:37], v[174:177], v[202:205], v[34:37]
	v_mfma_f32_16x16x32_bf16 v[22:25], v[166:169], v[210:213], v[22:25]
	v_mfma_f32_16x16x32_bf16 v[18:21], v[174:177], v[210:213], v[18:21]
	v_mfma_f32_16x16x32_bf16 v[6:9], v[166:169], v[218:221], v[6:9]
	v_mfma_f32_16x16x32_bf16 v[2:5], v[174:177], v[218:221], v[2:5]
	v_mfma_f32_16x16x32_bf16 v[54:57], v[170:173], v[198:201], v[54:57]
	v_mfma_f32_16x16x32_bf16 v[50:53], v[178:181], v[198:201], v[50:53]
	v_mfma_f32_16x16x32_bf16 v[38:41], v[170:173], v[206:209], v[38:41]
	v_mfma_f32_16x16x32_bf16 v[34:37], v[178:181], v[206:209], v[34:37]
	v_mfma_f32_16x16x32_bf16 v[22:25], v[170:173], v[214:217], v[22:25]
	v_mfma_f32_16x16x32_bf16 v[18:21], v[178:181], v[214:217], v[18:21]
	v_mfma_f32_16x16x32_bf16 v[6:9], v[170:173], v[222:225], v[6:9]
	v_mfma_f32_16x16x32_bf16 v[2:5], v[178:181], v[222:225], v[2:5]
	s_barrier
; #define PG8_STAGE(bufoff, gbase, voff) do { _Pragma("unroll") for (int _i = 0; _i < 2; ++_i) \
;         __builtin_amdgcn_global_load_lds((const unsigned*)((const char*)(gbase) + (voff)[_i]), (LAS unsigned*)(lds + (bufoff) + ldsw + _i * 8192), 16, 0, 0); } while (0)
; #define PG8_LDA(dst, b, h) do { _Pragma("unroll") for (int m = 0; m < 4; ++m) _Pragma("unroll") for (int k = 0; k < 2; ++k) dst[m][k] = *(const LAS bf16x8*)(lds + PG8_SA(b, h) + aoff + m * 2048 + k * 1024); } while (0)
; #define PG8_LDB(dst, b, h) do { _Pragma("unroll") for (int n = 0; n < 2; ++n) _Pragma("unroll") for (int k = 0; k < 2; ++k) dst[n][k] = *(const LAS bf16x8*)(lds + PG8_SB(b, h) + boff + n * 2048 + k * 1024); } while (0)
; #define PG8_MMA(ai, bj, At, Bt) do { __builtin_amdgcn_s_setprio(1); _Pragma("unroll") for (int m = 0; m < 4; ++m) _Pragma("unroll") for (int n = 0; n < 2; ++n) _Pragma("unroll") for (int k = 0; k < 2; ++k) \
;         acc[ai][bj][m][n] = __builtin_amdgcn_mfma_f32_16x16x32_bf16(Bt[n][k], At[m][k], acc[ai][bj][m][n], 0, 0, 0); __builtin_amdgcn_s_setprio(0); } while (0)
; #define PG8_WAIT_V(n) asm volatile("s_waitcnt vmcnt(" #n ")" ::: "memory")
; #define PG8_WAIT_L(n) asm volatile("s_waitcnt lgkmcnt(" #n ")" ::: "memory")
; #define PG8_BAR __builtin_amdgcn_s_barrier()
; #define PG8_SCHED __builtin_amdgcn_sched_barrier(0)
; template <class Epi>
; __device__ __forceinline__ void gemm_phase(LAS unsigned char* lds, const Gemm g, const StaticOrder& S, const Epi& E) {
;     ...
;             PG8_LDB(B0, 1, 0); PG8_LDB(B1, 1, 1); PG8_SCHED; PG8_LDA(At, 1, 0); PG8_STAGE(PG8_SA(0, 1), a2 + hstepA, voffA);
;             PG8_WAIT_V(8); PG8_WAIT_L(0); PG8_BAR; PG8_MMA(0, 0, At, B0); PG8_MMA(0, 1, At, B1); PG8_BAR; PG8_SCHED;
;             PG8_LDA(At, 1, 1); PG8_STAGE(PG8_SB(1, 0), b3, voffB); PG8_STAGE(PG8_SB(1, 1), b3 + hstepB, voffB); PG8_STAGE(PG8_SA(1, 0), a3, voffA);
;             PG8_WAIT_V(8); PG8_WAIT_L(0); PG8_BAR; PG8_MMA(1, 0, At, B0); PG8_MMA(1, 1, At, B1); PG8_BAR; PG8_SCHED;
;         }
;         if (wr == 0) PG8_BAR;
	s_setprio 0
	s_add_i32 s50, 0, 0x18000
	s_add_i32 s51, 0, 0x1c000
	v_add_u32_e32 v156, s50, v145
	v_add_u32_e32 v178, s51, v145
	ds_read_b128 v[140:143], v156
	ds_read_b128 v[148:151], v156 offset:1024
	ds_read_b128 v[152:155], v156 offset:2048
	ds_read_b128 v[156:159], v156 offset:3072
	ds_read_b128 v[166:169], v178
	ds_read_b128 v[170:173], v178 offset:1024
	ds_read_b128 v[174:177], v178 offset:2048
	ds_read_b128 v[178:181], v178 offset:3072
	s_add_u32 s34, s34, 0x80000
	s_addc_u32 s35, s35, 0
	s_mov_b32 m0, s36
	ds_read_b128 v[194:197], v147 offset:32768
	ds_read_b128 v[198:201], v147 offset:33792
	ds_read_b128 v[202:205], v147 offset:34816
	ds_read_b128 v[206:209], v147 offset:35840
	ds_read_b128 v[210:213], v147 offset:36864
	ds_read_b128 v[214:217], v147 offset:37888
	ds_read_b128 v[218:221], v147 offset:38912
	ds_read_b128 v[222:225], v147 offset:39936
	global_load_lds_dwordx4 v134, s[34:35]
	s_mov_b32 m0, s37
	s_nop 0
	global_load_lds_dwordx4 v132, s[34:35]
	s_waitcnt vmcnt(8)
	s_waitcnt lgkmcnt(0)
	s_setprio 1
	s_barrier
	v_mfma_f32_16x16x32_bf16 v[126:129], v[140:143], v[194:197], v[126:129]
	v_mfma_f32_16x16x32_bf16 v[122:125], v[152:155], v[194:197], v[122:125]
	v_mfma_f32_16x16x32_bf16 v[110:113], v[140:143], v[202:205], v[110:113]
	v_mfma_f32_16x16x32_bf16 v[106:109], v[152:155], v[202:205], v[106:109]
	v_mfma_f32_16x16x32_bf16 v[94:97], v[140:143], v[210:213], v[94:97]
	v_mfma_f32_16x16x32_bf16 v[90:93], v[152:155], v[210:213], v[90:93]
	v_mfma_f32_16x16x32_bf16 v[78:81], v[140:143], v[218:221], v[78:81]
	v_mfma_f32_16x16x32_bf16 v[74:77], v[152:155], v[218:221], v[74:77]
	v_mfma_f32_16x16x32_bf16 v[126:129], v[148:151], v[198:201], v[126:129]
	v_mfma_f32_16x16x32_bf16 v[122:125], v[156:159], v[198:201], v[122:125]
	v_mfma_f32_16x16x32_bf16 v[110:113], v[148:151], v[206:209], v[110:113]
	v_mfma_f32_16x16x32_bf16 v[106:109], v[156:159], v[206:209], v[106:109]
	v_mfma_f32_16x16x32_bf16 v[94:97], v[148:151], v[214:217], v[94:97]
	v_mfma_f32_16x16x32_bf16 v[90:93], v[156:159], v[214:217], v[90:93]
	v_mfma_f32_16x16x32_bf16 v[78:81], v[148:151], v[222:225], v[78:81]
	v_mfma_f32_16x16x32_bf16 v[74:77], v[156:159], v[222:225], v[74:77]
	v_mfma_f32_16x16x32_bf16 v[118:121], v[166:169], v[194:197], v[118:121]
	v_mfma_f32_16x16x32_bf16 v[114:117], v[174:177], v[194:197], v[114:117]
	v_mfma_f32_16x16x32_bf16 v[102:105], v[166:169], v[202:205], v[102:105]
	v_mfma_f32_16x16x32_bf16 v[98:101], v[174:177], v[202:205], v[98:101]
	v_mfma_f32_16x16x32_bf16 v[86:89], v[166:169], v[210:213], v[86:89]
	v_mfma_f32_16x16x32_bf16 v[82:85], v[174:177], v[210:213], v[82:85]
	v_mfma_f32_16x16x32_bf16 v[70:73], v[166:169], v[218:221], v[70:73]
	v_mfma_f32_16x16x32_bf16 v[66:69], v[174:177], v[218:221], v[66:69]
	v_mfma_f32_16x16x32_bf16 v[118:121], v[170:173], v[198:201], v[118:121]
	v_mfma_f32_16x16x32_bf16 v[114:117], v[178:181], v[198:201], v[114:117]
	v_mfma_f32_16x16x32_bf16 v[102:105], v[170:173], v[206:209], v[102:105]
	v_mfma_f32_16x16x32_bf16 v[98:101], v[178:181], v[206:209], v[98:101]
	v_mfma_f32_16x16x32_bf16 v[86:89], v[170:173], v[214:217], v[86:89]
	v_mfma_f32_16x16x32_bf16 v[82:85], v[178:181], v[214:217], v[82:85]
	v_mfma_f32_16x16x32_bf16 v[70:73], v[170:173], v[222:225], v[70:73]
	v_mfma_f32_16x16x32_bf16 v[66:69], v[178:181], v[222:225], v[66:69]
	s_barrier
	s_setprio 0
	s_add_i32 s32, s50, s23
	s_add_u32 s26, s26, 0x80
	s_addc_u32 s27, s27, 0
	s_mov_b32 m0, s32
	ds_read_b128 v[194:197], v147 offset:49152
	ds_read_b128 v[198:201], v147 offset:50176
	ds_read_b128 v[202:205], v147 offset:51200
	ds_read_b128 v[206:209], v147 offset:52224
	ds_read_b128 v[210:213], v147 offset:53248
	ds_read_b128 v[214:217], v147 offset:54272
	ds_read_b128 v[218:221], v147 offset:55296
	ds_read_b128 v[222:225], v147 offset:56320
	global_load_lds_dwordx4 v0, s[26:27]
	s_add_i32 m0, s32, 0x2000
	s_add_i32 s32, s51, s23
	global_load_lds_dwordx4 v130, s[26:27]
	s_add_u32 s26, s26, 0x80000
	s_addc_u32 s27, s27, 0
	s_mov_b32 m0, s32
	s_nop 0
	global_load_lds_dwordx4 v0, s[26:27]
	s_add_i32 m0, s32, 0x2000
	s_sub_u32 s34, s34, 0x7ff80
	s_subb_u32 s35, s35, 0
	global_load_lds_dwordx4 v130, s[26:27]
	s_mov_b32 m0, s38
	s_nop 0
	global_load_lds_dwordx4 v134, s[34:35]
	s_mov_b32 m0, s39
	s_nop 0
	global_load_lds_dwordx4 v132, s[34:35]
	s_waitcnt vmcnt(8)
	s_waitcnt lgkmcnt(0)
	s_setprio 1
	s_barrier
	v_mfma_f32_16x16x32_bf16 v[62:65], v[140:143], v[194:197], v[62:65]
	v_mfma_f32_16x16x32_bf16 v[58:61], v[152:155], v[194:197], v[58:61]
	v_mfma_f32_16x16x32_bf16 v[46:49], v[140:143], v[202:205], v[46:49]
	v_mfma_f32_16x16x32_bf16 v[42:45], v[152:155], v[202:205], v[42:45]
	v_mfma_f32_16x16x32_bf16 v[30:33], v[140:143], v[210:213], v[30:33]
	v_mfma_f32_16x16x32_bf16 v[26:29], v[152:155], v[210:213], v[26:29]
	v_mfma_f32_16x16x32_bf16 v[14:17], v[140:143], v[218:221], v[14:17]
	v_mfma_f32_16x16x32_bf16 v[10:13], v[152:155], v[218:221], v[10:13]
	v_mfma_f32_16x16x32_bf16 v[62:65], v[148:151], v[198:201], v[62:65]
	v_mfma_f32_16x16x32_bf16 v[58:61], v[156:159], v[198:201], v[58:61]
	v_mfma_f32_16x16x32_bf16 v[46:49], v[148:151], v[206:209], v[46:49]
	v_mfma_f32_16x16x32_bf16 v[42:45], v[156:159], v[206:209], v[42:45]
	v_mfma_f32_16x16x32_bf16 v[30:33], v[148:151], v[214:217], v[30:33]
	v_mfma_f32_16x16x32_bf16 v[26:29], v[156:159], v[214:217], v[26:29]
	v_mfma_f32_16x16x32_bf16 v[14:17], v[148:151], v[222:225], v[14:17]
	v_mfma_f32_16x16x32_bf16 v[10:13], v[156:159], v[222:225], v[10:13]
	v_mfma_f32_16x16x32_bf16 v[54:57], v[166:169], v[194:197], v[54:57]
	v_mfma_f32_16x16x32_bf16 v[50:53], v[174:177], v[194:197], v[50:53]
	v_mfma_f32_16x16x32_bf16 v[38:41], v[166:169], v[202:205], v[38:41]
	v_mfma_f32_16x16x32_bf16 v[34:37], v[174:177], v[202:205], v[34:37]
	v_mfma_f32_16x16x32_bf16 v[22:25], v[166:169], v[210:213], v[22:25]
	v_mfma_f32_16x16x32_bf16 v[18:21], v[174:177], v[210:213], v[18:21]
	v_mfma_f32_16x16x32_bf16 v[6:9], v[166:169], v[218:221], v[6:9]
	v_mfma_f32_16x16x32_bf16 v[2:5], v[174:177], v[218:221], v[2:5]
	v_mfma_f32_16x16x32_bf16 v[54:57], v[170:173], v[198:201], v[54:57]
	v_mfma_f32_16x16x32_bf16 v[50:53], v[178:181], v[198:201], v[50:53]
	v_mfma_f32_16x16x32_bf16 v[38:41], v[170:173], v[206:209], v[38:41]
	v_mfma_f32_16x16x32_bf16 v[34:37], v[178:181], v[206:209], v[34:37]
	v_mfma_f32_16x16x32_bf16 v[22:25], v[170:173], v[214:217], v[22:25]
	v_mfma_f32_16x16x32_bf16 v[18:21], v[178:181], v[214:217], v[18:21]
	v_mfma_f32_16x16x32_bf16 v[6:9], v[170:173], v[222:225], v[6:9]
	v_mfma_f32_16x16x32_bf16 v[2:5], v[178:181], v[222:225], v[2:5]
	s_barrier
	s_setprio 0
	s_add_i32 s49, s49, 2
	s_add_u32 s24, s24, 0x100
	s_addc_u32 s25, s25, 0
	s_add_u32 s47, s47, 0x100
	s_addc_u32 s48, s48, 0
	s_cmp_gt_u32 s49, 29
	s_cbranch_scc0 .LBB0_295
	s_and_b64 vcc, exec, s[8:9]
	s_cbranch_vccz .LBB0_298
	s_barrier
